# v43 + retention state chains split over 2 WGs each (rows 0-127/128-255, WGs 0..63), hyena conv on WGs 64..255
# baseline (speedup 1.0000x reference)
; #define TM_BEGIN(k) do { if ((TIMEMASK >> (k)) & 1u) tm_t0 = __builtin_amdgcn_s_memrealtime(); } while (0)
; #define GAS __attribute__((address_space(1)))
; #define REP(k) _Pragma("unroll 1") for (int _r = 0; _r < (((DUPMASK >> (k)) & 1u) ? 2 : 1); ++_r)
; #define LAUNDER() do { int _t = F.tid; asm volatile("" : "+v"(_t)); F.tid = _t; F.lane = _t & 63; F.wave = __builtin_amdgcn_readfirstlane(_t >> 6); \
;         asm volatile("" : "+s"(ap)); GAS unsigned char* _w = (GAS unsigned char*)ap->ws; asm volatile("" : "+s"(_w)); F.ws = _w; ws = _w; } while (0)
; __global__ void __launch_bounds__(512, 2) mk_fwd(Args args_unused) {
;     ...
; #pragma unroll 1
;     for (int l = 0; l < DEPTH; ++l) {
;         const int p0 = 3 + l * PH_PER_LAYER;
;         TM_BEGIN(0);
;         if (IN(p0 + 0)) REP(0) {
;             LAUNDER();
;             pg8::BigOrder S; S.init(ws + WS_XM, (const GAS bf16_t*)(ws + WS_WIN) + (size_t)l * DIN * D, D, D, M, DIN, F.G, F.blk);
;             pg8::EpiBf16<0> E{(GAS bf16_t*)(ws + WS_Z), DIN, ((const GAS float*)ap->in[I_BIN]) + (size_t)l * DIN};
;             pg8::gemm_phase<pg8::EpiBf16<0>, pg8::BigOrder, false, true>(F.lds, F.tid, pg8::Gemm{D, D, D}, S, E);
;             if (l + 1 < DEPTH && F.G == 256 && F.blk >= 192) { LAUNDER(); convert_layer(F, ap, l + 1, (F.blk - 192) * 8 + F.wave, 64 * 8, 12288, 15360); }
.LBB0_448:
	s_cmpk_lt_i32 s2, 0x6c0
	s_cselect_b64 s[4:5], -1, 0
	v_writelane_b32 v253, s4, 2
	s_ashr_i32 s80, s2, 31
	s_ashr_i32 s83, s3, 31
	v_writelane_b32 v253, s5, 3
	s_lshr_b32 s4, s80, 29
	s_add_i32 s4, s2, s4
	s_ashr_i32 s8, s4, 3
	s_and_b32 s4, s4, -8
	s_sub_i32 s14, s2, s4
	s_cmpk_eq_i32 s3, 0x100
	s_cselect_b64 s[4:5], -1, 0
	v_writelane_b32 v253, s4, 4
	s_cmpk_lg_i32 s3, 0x100
	v_mov_b32_e32 v203, 0
	v_writelane_b32 v253, s5, 5
	s_cselect_b64 s[4:5], -1, 0
	v_writelane_b32 v253, s4, 6
	s_cmpk_gt_i32 s2, 0xbf
	s_mov_b32 s57, 0
	v_writelane_b32 v253, s5, 7
	s_cselect_b64 s[4:5], -1, 0
	v_writelane_b32 v253, s4, 8
	s_lshl_b32 s9, s2, 3
	v_mov_b32_e32 v205, 1
	v_writelane_b32 v253, s5, 9
	s_add_i32 s4, s9, 0xfffffa00
	s_add_u32 s92, s28, 0x4200
	s_addc_u32 s93, s29, 0
	v_writelane_b32 v253, s4, 10
	s_add_u32 s4, s28, 0x4400
	s_addc_u32 s5, s29, 0
	v_writelane_b32 v253, s4, 11
	v_mov_b32_e32 v204, 0x3ecc95a3
	v_mov_b32_e32 v228, 0x358637bd
	v_writelane_b32 v253, s5, 12
	s_add_u32 s4, s28, 0x4500
	s_addc_u32 s5, s29, 0
	v_writelane_b32 v253, s4, 13
	v_mov_b32_e32 v229, 0x260
	v_mov_b32_e32 v230, 0x3727c5ac
	v_writelane_b32 v253, s5, 14
	s_add_u32 s4, s28, 0x4600
	s_addc_u32 s5, s29, 0
	v_writelane_b32 v253, s4, 15
	v_mov_b32_e32 v231, 0x7ff
	v_mov_b32_e32 v232, 0xff
	v_writelane_b32 v253, s5, 16
	s_add_u32 s4, s28, 0x4700
	s_addc_u32 s5, s29, 0
	v_writelane_b32 v253, s4, 17
	v_mov_b32_e32 v233, 0x800
	v_mov_b32_e32 v234, 0x100
	v_writelane_b32 v253, s5, 18
	s_add_u32 s4, s28, 0x4800
	s_addc_u32 s5, s29, 0
	v_writelane_b32 v253, s4, 19
	v_mov_b32_e32 v235, 0x7f800000
	v_mov_b32_e32 v236, 0x7fc00000
	v_writelane_b32 v253, s5, 20
	s_add_u32 s4, s28, 0x4900
	s_addc_u32 s5, s29, 0
	v_writelane_b32 v253, s4, 21
	v_mov_b32_e32 v237, 0xff800000
	v_mov_b32_e32 v238, 0x600
	v_writelane_b32 v253, s5, 22
	s_add_u32 s4, s28, 0x4a00
	s_addc_u32 s5, s29, 0
	v_writelane_b32 v253, s4, 23
	v_mov_b32_e32 v239, 0x42800000
	v_not_b32_e32 v240, 63
	v_writelane_b32 v253, s5, 24
	s_add_u32 s4, s28, 0x4b00
	s_addc_u32 s5, s29, 0
	v_writelane_b32 v253, s4, 25
	v_mov_b32_e32 v206, 0x3f317218
	v_mov_b32_e32 v241, 0x60000
	v_writelane_b32 v253, s5, 26
	s_add_u32 s4, s28, 0x4c00
	s_addc_u32 s5, s29, 0
	v_writelane_b32 v253, s4, 27
	v_mov_b32_e32 v208, v203
	v_mov_b32_e32 v209, v203
	v_writelane_b32 v253, s5, 28
	s_add_u32 s4, s28, 0x4d00
	s_addc_u32 s5, s29, 0
	v_writelane_b32 v253, s4, 29
	v_mov_b32_e32 v210, v203
	v_mov_b32_e32 v211, v203
	v_writelane_b32 v253, s5, 30
	s_add_u32 s4, s28, 0x4e00
	s_addc_u32 s5, s29, 0
	v_writelane_b32 v253, s4, 31
	v_mov_b32_e32 v252, 0x9b0
	v_mov_b64_e32 v[250:251], 0x48
	v_writelane_b32 v253, s5, 32
	s_add_u32 s4, s28, 0x4f00
	s_addc_u32 s5, s29, 0
	v_writelane_b32 v253, s4, 33
	v_mov_b64_e32 v[242:243], 0x47
	v_mov_b32_e32 v245, 0x477fe000
	v_writelane_b32 v253, s5, 34
	s_add_u32 s4, s28, 0x5000
	s_addc_u32 s5, s29, 0
	v_writelane_b32 v253, s4, 35
	v_mov_b64_e32 v[212:213], 0x1e8481
	s_movk_i32 s67, 0x2000
	v_writelane_b32 v253, s5, 36
	s_add_u32 s4, s28, 0x5100
	s_addc_u32 s5, s29, 0
	v_writelane_b32 v253, s4, 37
	s_movk_i32 s74, 0x6000
	s_movk_i32 s75, 0x1000
	v_writelane_b32 v253, s5, 38
	s_add_u32 s4, s28, 0x5200
	s_addc_u32 s5, s29, 0
	v_writelane_b32 v253, s4, 39
	s_mov_b32 s76, 0xc2fc0000
	s_movk_i32 s77, 0xfe00
	v_writelane_b32 v253, s5, 40
	s_add_u32 s4, s28, 0x5300
	s_addc_u32 s5, s29, 0
	v_writelane_b32 v253, s4, 41
	s_cmp_eq_u32 s33, 15
	s_movk_i32 s85, 0x7d7
	v_writelane_b32 v253, s5, 42
	s_cselect_b64 s[4:5], -1, 0
	v_writelane_b32 v253, s4, 43
	s_cmp_eq_u32 s33, 14
	s_mov_b32 s78, 0x1000706
	v_writelane_b32 v253, s5, 44
	s_cselect_b64 s[4:5], -1, 0
	v_writelane_b32 v253, s4, 45
	s_cmp_eq_u32 s33, 13
	s_movk_i32 s79, 0x1ff
	v_writelane_b32 v253, s5, 46
	s_cselect_b64 s[4:5], -1, 0
	v_writelane_b32 v253, s4, 47
	s_cmp_eq_u32 s33, 12
	s_movk_i32 s90, 0x370
	v_writelane_b32 v253, s5, 48
	s_cselect_b64 s[4:5], -1, 0
	v_writelane_b32 v253, s4, 49
	s_cmp_eq_u32 s33, 11
	s_movk_i32 s81, 0xfe3f
	v_writelane_b32 v253, s5, 50
	s_cselect_b64 s[4:5], -1, 0
	v_writelane_b32 v253, s4, 51
	s_cmp_eq_u32 s33, 10
	s_movk_i32 s86, 0xfe7f
	v_writelane_b32 v253, s5, 52
	s_cselect_b64 s[4:5], -1, 0
	v_writelane_b32 v253, s4, 53
	s_cmp_eq_u32 s33, 9
	s_mov_b32 s84, 0xc77fe000
	v_writelane_b32 v253, s5, 54
	s_cselect_b64 s[4:5], -1, 0
	v_writelane_b32 v253, s4, 55
	s_cmp_eq_u32 s33, 8
	s_mov_b64 s[20:21], 0x2000
	v_writelane_b32 v253, s5, 56
	s_cselect_b64 s[4:5], -1, 0
	v_writelane_b32 v253, s4, 57
	s_cmp_eq_u32 s33, 7
	s_mov_b32 s66, 0x3fd744fd
	v_writelane_b32 v253, s5, 58
	s_cselect_b64 s[4:5], -1, 0
	v_writelane_b32 v253, s4, 59
	s_cmp_eq_u32 s33, 6
	s_nop 0
	v_writelane_b32 v253, s5, 60
	s_cselect_b64 s[4:5], -1, 0
	v_writelane_b32 v253, s4, 61
	s_cmp_eq_u32 s33, 5
	s_nop 0
	v_writelane_b32 v253, s5, 62
	s_cselect_b64 s[4:5], -1, 0
	v_writelane_b32 v253, s4, 63
	s_cmp_eq_u32 s33, 4
	s_nop 0
	v_writelane_b32 v254, s5, 0
	s_cselect_b64 s[4:5], -1, 0
	v_writelane_b32 v254, s4, 1
	s_cmp_eq_u32 s33, 3
	s_nop 0
	v_writelane_b32 v254, s5, 2
	s_cselect_b64 s[4:5], -1, 0
	v_writelane_b32 v254, s4, 3
	s_cmp_eq_u32 s33, 2
	s_nop 0
	v_writelane_b32 v254, s5, 4
	s_cselect_b64 s[4:5], -1, 0
	v_writelane_b32 v254, s4, 5
	s_cmp_eq_u32 s33, 1
	s_nop 0
	v_writelane_b32 v254, s5, 6
	s_cselect_b64 s[4:5], -1, 0
	v_writelane_b32 v254, s4, 7
	s_cmp_eq_u32 s33, 0
	s_nop 0
	v_writelane_b32 v254, s5, 8
	s_cselect_b64 s[4:5], -1, 0
	v_writelane_b32 v254, s4, 9
	s_nop 1
	v_writelane_b32 v254, s5, 10
	s_lshl_b32 s4, s33, 8
	s_add_u32 s4, s30, s4
	s_addc_u32 s5, s31, 0
	s_add_u32 s6, s4, 0x1400
	s_addc_u32 s7, s5, 0
	v_writelane_b32 v254, s6, 11
; #define LAS __attribute__((address_space(3)))
; #define GAS __attribute__((address_space(1)))
; __device__ __forceinline__ float ret_lg2(const GAS float* rdec, int l, int dirh) { const float p = rdec[l * 8 + dirh]; return log1pf(-expf(p)) * 1.4426950408889634f; }
; #define REP(k) _Pragma("unroll 1") for (int _r = 0; _r < (((DUPMASK >> (k)) & 1u) ? 2 : 1); ++_r)
; #define LAUNDER() do { int _t = F.tid; asm volatile("" : "+v"(_t)); F.tid = _t; F.lane = _t & 63; F.wave = __builtin_amdgcn_readfirstlane(_t >> 6); \
;         asm volatile("" : "+s"(ap)); GAS unsigned char* _w = (GAS unsigned char*)ap->ws; asm volatile("" : "+s"(_w)); F.ws = _w; ws = _w; } while (0)
;         const int s = i & 7, dir = ch & 1, bh = ch >> 1; u.z = bh * 9 + (dir == 0 ? s : (s == 0 ? 0 : 9 - s)); u.pn = dir; u.pm = s; return true; }
; __global__ void __launch_bounds__(512, 2) mk_fwd(Args args_unused) {
;     ...
;                 ChainOrder S{(const GAS char*)(ws + WS_BBUF), (const GAS char*)(ws + WS_KT), F.G, F.blk};
;                 if (F.tid < 8) ((LAS float*)(F.lds + RING_BYTES))[F.tid] = exp2f(256.0f * ret_lg2((const GAS float*)ap->in[I_RDEC], l, F.tid));
;                 __syncthreads();
;                 pg8::EpiChain E{(GAS bf16_t*)(ws + WS_BBUF), (const LAS float*)(F.lds + RING_BYTES)};
;                 pg8::gemm_phase<pg8::EpiChain, ChainOrder, true, true>(F.lds, F.tid, pg8::Gemm{768, 256, 256}, S, E);
;             }
;             {
;                 LAUNDER();
;                 ScoresOrder S{(const GAS char*)(ws + WS_QR), (const GAS char*)(ws + WS_KRB), F.G, (F.blk + 160) % F.G};
;                 pg8::EpiScores E{(GAS bf16_t*)(ws + WS_ABUF), ((const GAS float*)ap->in[I_RDEC]) + l * 8};
;                 pg8::gemm_phase<pg8::EpiScores, ScoresOrder, true, true>(F.lds, F.tid, pg8::Gemm{1024, 1024, 256}, S, E);
;             }
;             REP(15) { LAUNDER(); if (F.G == 256) { if (F.blk >= 32) conv_phase(F, ap, l, F.blk - 32, 224); } else conv_phase(F, ap, l, F.blk, F.G); }
	s_add_u32 s4, s4, 0x2400
	s_addc_u32 s5, s5, 0
	v_writelane_b32 v254, s7, 12
	v_writelane_b32 v254, s4, 13
	s_movk_i32 s33, 0x600
	s_mov_b64 s[30:31], 0x20000
	v_writelane_b32 v254, s5, 14
	s_add_u32 s4, s28, 0x7400
	s_addc_u32 s5, s29, 0
	v_writelane_b32 v254, s4, 15
	s_nop 1
	v_writelane_b32 v254, s5, 16
	s_add_u32 s4, s28, 0x7500
	s_addc_u32 s5, s29, 0
	s_lshl_b32 s36, s3, 3
	v_writelane_b32 v254, s4, 17
	s_cmp_lt_i32 s2, 64
	s_mov_b64 s[28:29], 0x1000
	v_writelane_b32 v254, s5, 18
	s_cselect_b64 s[4:5], -1, 0
	v_writelane_b32 v254, s4, 19
	s_add_i32 s10, s2, 0xa0
	s_nop 0
	v_writelane_b32 v254, s5, 20
	s_and_b32 s4, s2, 31
	s_ashr_i32 s4, s4, 1
	s_and_b32 s5, s2, 1
	s_mul_i32 s12, s4, 9
	v_writelane_b32 v254, s5, 21
	s_lshl_b32 s5, s5, 17
	v_writelane_b32 v254, s5, 22
	s_mov_b32 s6, s12
	s_ashr_i32 s13, s12, 31
	v_writelane_b32 v254, s6, 23
	s_mul_i32 s4, s4, 0x360000
	s_nop 0
	v_writelane_b32 v254, s7, 24
	s_lshl_b64 s[6:7], s[12:13], 18
	v_writelane_b32 v254, s6, 25
	s_cmpk_lt_i32 s2, 0x200
	s_nop 0
	v_writelane_b32 v254, s7, 26
	s_cselect_b64 s[6:7], -1, 0
	s_not_b32 s5, s2
	v_writelane_b32 v254, s6, 27
	s_add_i32 s5, s3, s5
	s_cmpk_lt_i32 s5, 0x200
	v_writelane_b32 v254, s7, 28
	v_writelane_b32 v254, s5, 29
	s_cselect_b64 s[6:7], -1, 0
	v_writelane_b32 v254, s6, 30
	s_cmp_gt_i32 s2, 31
	s_nop 0
	v_writelane_b32 v254, s7, 31
	s_cselect_b64 s[6:7], -1, 0
	v_writelane_b32 v254, s6, 32
	s_sub_i32 s5, s2, 64
	s_cmpk_lt_u32 s5, 0x200
	v_writelane_b32 v254, s7, 33
	v_writelane_b32 v254, s5, 34
	s_cselect_b64 s[6:7], -1, 0
	v_writelane_b32 v254, s6, 35
	s_sub_i32 s5, 0xff, s2
	s_cmpk_lt_i32 s2, 0x90
	v_writelane_b32 v254, s7, 36
	v_writelane_b32 v254, s5, 37
	s_cselect_b64 s[6:7], -1, 0
	v_writelane_b32 v254, s6, 38
	s_cmpk_lt_i32 s2, 0x240
	s_nop 0
	v_writelane_b32 v254, s7, 39
	s_cselect_b64 s[6:7], -1, 0
	v_writelane_b32 v254, s6, 40
	s_cmpk_gt_i32 s2, 0x8f
	s_nop 0
	v_writelane_b32 v254, s7, 41
	s_cselect_b64 s[6:7], -1, 0
	s_add_i32 s5, s2, 0xffffff70
	v_writelane_b32 v254, s6, 42
	s_cmpk_lt_u32 s5, 0x240
	s_nop 0
	v_writelane_b32 v254, s7, 43
	s_cselect_b64 s[6:7], -1, 0
	v_writelane_b32 v254, s6, 44
	s_add_i32 s11, s2, 0x48
	s_lshl_b32 s37, s3, 2
	v_writelane_b32 v254, s7, 45
	s_and_b32 s6, s2, 7
	v_writelane_b32 v254, s6, 46
	s_lshl_b32 s6, s6, 2
	s_ashr_i32 s7, s2, 6
	s_add_i32 s6, s6, s7
	s_add_i32 s7, s7, 32
	v_writelane_b32 v254, s7, 47
	s_add_i32 s7, s9, 0xffffff00
	v_writelane_b32 v254, s7, 48
	v_writelane_b32 v254, s6, 49
	s_add_i32 s6, s6, 4
	v_writelane_b32 v254, s6, 50
	s_bfe_u32 s6, s2, 0x30003
	s_lshl_b32 s7, s6, 20
	s_cmpk_gt_i32 s2, 0x7f
	v_writelane_b32 v254, s7, 51
	s_cselect_b64 s[12:13], -1, 0
	v_writelane_b32 v254, s12, 52
	s_add_i32 s7, s9, 0xfffffc00
	s_nop 0
	v_writelane_b32 v254, s13, 53
	v_writelane_b32 v254, s9, 54
	v_writelane_b32 v254, s7, 55
	v_writelane_b32 v254, s6, 56
	s_lshl_b32 s6, s6, 22
	v_writelane_b32 v254, s6, 57
	s_cmp_lt_i32 s14, 0
	s_movk_i32 s6, 0xd9
	s_cselect_b32 s6, s6, 0xd8
	s_mul_i32 s6, s14, s6
	s_add_i32 s6, s6, s8
	s_mul_hi_i32 s7, s6, 0x2aaaaaab
	v_writelane_b32 v254, s8, 58
	s_lshr_b32 s8, s7, 31
	s_ashr_i32 s7, s7, 6
	s_add_i32 s7, s7, s8
	s_mul_i32 s8, s7, 0x180
	s_lshl_b32 s9, s7, 3
	s_sub_i32 s8, s6, s8
	s_sub_i32 s6, 36, s9
	s_min_u32 s12, s6, 8
	v_cvt_f32_ubyte0_e32 v2, s12
	v_cvt_f32_i32_e32 v1, s8
	v_rcp_iflag_f32_e32 v3, v2
	s_ashr_i32 s6, s8, 30
	s_or_b32 s13, s6, 1
	v_writelane_b32 v254, s14, 59
	v_mul_f32_e32 v3, v1, v3
	v_trunc_f32_e32 v3, v3
	v_fma_f32 v1, -v3, v2, v1
	s_lshr_b32 s6, s14, 31
	v_writelane_b32 v254, s6, 60
	v_cmp_ge_f32_e64 s[6:7], |v1|, v2
	v_cvt_i32_f32_e32 v1, v3
	s_and_b64 s[6:7], s[6:7], exec
	s_cselect_b32 s6, s13, 0
	v_readfirstlane_b32 s7, v1
	s_add_i32 s6, s7, s6
	s_mul_i32 s7, s6, s12
	s_abs_i32 s12, s3
	v_cvt_f32_u32_e32 v1, s12
	s_sub_i32 s7, s8, s7
	s_sub_i32 s8, 0, s12
	s_sext_i32_i16 s7, s7
	v_rcp_iflag_f32_e32 v1, v1
	s_add_i32 s16, s9, s7
	s_ashr_i32 s17, s16, 31
	v_mul_f32_e32 v1, 0x4f7ffffe, v1
	v_cvt_u32_f32_e32 v1, v1
	s_nop 0
	v_readfirstlane_b32 s13, v1
	s_mul_i32 s8, s8, s13
	s_mul_hi_u32 s8, s13, s8
	s_add_i32 s13, s13, s8
	s_abs_i32 s8, s10
; #define TM_BEGIN(k) do { if ((TIMEMASK >> (k)) & 1u) tm_t0 = __builtin_amdgcn_s_memrealtime(); } while (0)
; #define TM_END(k) do { if ((TIMEMASK >> (k)) & 1u) tm_acc += __builtin_amdgcn_s_memrealtime() - tm_t0; } while (0)
; #define GAS __attribute__((address_space(1)))
;     __device__ __forceinline__ const GAS char* aptr(const Unit& u) const { return A + (size_t)u.pm * astep + koff(u); }
;     __device__ __forceinline__ const GAS char* bptr(const Unit& u) const { return B + (size_t)u.pn * bstep + koff(u); }
; #define SEAM(k) do { if (IN(k) && IN((k) + 1)) GRID_BAR(); } while (0)
;     __device__ __forceinline__ size_t rowoff(const pg8::Unit& u) const { const int bh = u.z / 9, ci = u.z % 9; return ((size_t)chunk_row0(bh >> 2, ci) * 1024 + (bh & 3) * 256) * 2; }
;     __device__ __forceinline__ const GAS char* aptr(const pg8::Unit& u) const { return Q + rowoff(u); }
;     __device__ __forceinline__ const GAS char* bptr(const pg8::Unit& u) const { return K + rowoff(u); }
; __global__ void __launch_bounds__(512, 2) mk_fwd(Args args_unused) {
;     ...
;                 ScoresOrder S{(const GAS char*)(ws + WS_QR), (const GAS char*)(ws + WS_KRB), F.G, (F.blk + 160) % F.G};
;                 pg8::EpiScores E{(GAS bf16_t*)(ws + WS_ABUF), ((const GAS float*)ap->in[I_RDEC]) + l * 8};
;                 pg8::gemm_phase<pg8::EpiScores, ScoresOrder, true, true>(F.lds, F.tid, pg8::Gemm{1024, 1024, 256}, S, E);
;             }
;             REP(15) { LAUNDER(); if (F.G == 256) { if (F.blk >= 32) conv_phase(F, ap, l, F.blk - 32, 224); } else conv_phase(F, ap, l, F.blk, F.G); }
;         }
;         SEAM(p0 + 2); TM_END(2);
;         TM_BEGIN(4);
;         if (IN(p0 + 3)) {
;             LAUNDER();
;             OutOrder S{(const GAS char*)(ws + WS_ABUF), (const GAS char*)(ws + WS_BBUF), F.G, F.blk};
;             pg8::EpiOutGn E{(const GAS bf16_t*)(ws + WS_Z), (GAS bf16_t*)(ws + WS_Y), F.lds + RING_BYTES};
;             pg8::gemm_phase<pg8::EpiOutGn, OutOrder, true, true>(F.lds, F.tid, pg8::Gemm{768, 768, 768}, S, E);
;             if (F.G == 256) { if (F.blk >= 144) { LAUNDER(); yt_phase(F, F.blk - 144, 112); } } else { LAUNDER(); yt_phase(F, F.blk, F.G); }
;             {
;                 LAUNDER();
;                 pg8::BigOrder S; S.init(ws + WS_POOL, (const GAS bf16_t*)(ws + WS_WPT) + (size_t)l * 512 * 512, 512, 512, M, 512, F.G, (F.blk + 72) % F.G);
	s_mul_hi_u32 s14, s8, s13
	s_mul_i32 s14, s14, s12
	s_sub_i32 s14, s8, s14
	s_bfe_i64 s[8:9], s[6:7], 0x100000
	s_lshl_b64 s[8:9], s[8:9], 20
	v_writelane_b32 v254, s8, 61
	s_ashr_i32 s7, s10, 31
	s_mov_b32 s10, s16
	v_writelane_b32 v254, s9, 62
	s_sub_i32 s8, s14, s12
	s_lshl_b64 s[16:17], s[16:17], 20
	s_cmp_ge_u32 s14, s12
	s_cselect_b32 s8, s8, s14
	s_sub_i32 s9, s8, s12
	s_cmp_ge_u32 s8, s12
	s_cselect_b32 s8, s9, s8
	s_xor_b32 s8, s8, s7
	v_writelane_b32 v254, s10, 63
	s_sub_i32 s9, s8, s7
	s_cmpk_lt_i32 s9, 0x90
	v_writelane_b32 v255, s11, 0
	v_writelane_b32 v255, s16, 1
	s_mul_hi_i32 s7, s9, 0x38e38e39
	s_cselect_b64 s[14:15], -1, 0
	v_writelane_b32 v255, s17, 2
	s_lshr_b32 s8, s7, 31
	s_ashr_i32 s7, s7, 1
	v_writelane_b32 v255, s14, 3
	s_add_i32 s7, s7, s8
	s_mul_i32 s8, s7, 9
	v_writelane_b32 v255, s15, 4
	v_writelane_b32 v255, s9, 5
	s_sub_i32 s8, s9, s8
	s_ashr_i32 s9, s7, 2
	s_cmp_lg_u32 s8, 0
	s_cselect_b64 s[14:15], -1, 0
	s_lshl_b32 s8, s8, 8
	s_lshl_b32 s10, s9, 11
	v_writelane_b32 v255, s14, 6
	s_add_i32 s8, s8, s10
	s_abs_i32 s10, s11
	v_writelane_b32 v255, s15, 7
	s_mul_hi_u32 s13, s10, s13
	s_addk_i32 s8, 0x300
	s_mul_i32 s13, s13, s12
	v_writelane_b32 v255, s8, 8
	s_lshl_b32 s8, s9, 8
	s_lshl_b32 s7, s7, 9
	s_sub_i32 s10, s10, s13
	v_writelane_b32 v255, s8, 9
	s_and_b32 s7, s7, 0x600
	v_writelane_b32 v255, s7, 10
	s_ashr_i32 s7, s11, 31
	s_sub_i32 s8, s10, s12
	s_cmp_ge_u32 s10, s12
	s_cselect_b32 s8, s8, s10
	s_sub_i32 s9, s8, s12
	s_cmp_ge_u32 s8, s12
	s_cselect_b32 s8, s9, s8
	s_xor_b32 s8, s8, s7
	s_sub_i32 s9, s8, s7
	s_cmpk_lt_i32 s9, 0x48
	s_cselect_b64 s[10:11], -1, 0
	v_writelane_b32 v255, s10, 11
	s_ashr_i32 s7, s9, 31
	s_sext_i32_i16 s6, s6
	v_writelane_b32 v255, s11, 12
	v_writelane_b32 v255, s7, 13
	s_lshr_b32 s7, s7, 29
	s_add_i32 s7, s9, s7
	s_ashr_i32 s8, s7, 3
	s_and_b32 s7, s7, -8
	s_sub_i32 s7, s9, s7
	s_cmp_lt_i32 s7, 0
	v_writelane_b32 v255, s9, 14
	s_cselect_b32 s9, 10, 9
	s_mul_i32 s7, s7, s9
	s_add_i32 s7, s7, s8
	s_ashr_i32 s8, s7, 31
	s_lshr_b32 s8, s8, 28
	s_add_i32 s8, s7, s8
	s_and_b32 s9, s8, -16
	s_ashr_i32 s8, s8, 4
	s_lshl_b32 s10, s8, 3
	s_sub_i32 s8, 36, s10
	s_min_u32 s11, s8, 8
	s_sub_i32 s7, s7, s9
	v_cvt_f32_ubyte0_e32 v2, s11
	v_cvt_f32_i32_e32 v1, s7
	v_rcp_iflag_f32_e32 v3, v2
	s_ashr_i32 s8, s7, 30
	s_or_b32 s12, s8, 1
	v_writelane_b32 v255, s6, 15
	v_mul_f32_e32 v3, v1, v3
	v_trunc_f32_e32 v3, v3
	v_fma_f32 v1, -v3, v2, v1
	v_cmp_ge_f32_e64 s[8:9], |v1|, v2
	v_cvt_i32_f32_e32 v1, v3
	s_and_b64 s[8:9], s[8:9], exec
	s_cselect_b32 s6, s12, 0
	v_writelane_b32 v255, s4, 16
	v_readfirstlane_b32 s8, v1
	s_add_i32 s6, s8, s6
	s_mul_i32 s8, s6, s11
	s_sub_i32 s7, s7, s8
	s_sext_i32_i8 s4, s7
	s_add_i32 s8, s10, s4
	s_sext_i32_i8 s4, s6
	s_bfe_i64 s[6:7], s[6:7], 0x80000
	v_writelane_b32 v255, s4, 17
	s_lshl_b64 s[6:7], s[6:7], 18
	v_writelane_b32 v255, s6, 18
	s_lshr_b32 s4, s5, 4
	s_lshl_b32 s5, s3, 4
	v_writelane_b32 v255, s7, 19
	v_writelane_b32 v255, s4, 20
	v_writelane_b32 v255, s5, 21
	s_lshl_b32 s6, s3, 7
	v_writelane_b32 v255, s6, 22
	s_add_i32 s6, s2, 0xffffff00
	s_lshl_b32 s4, s2, 4
	v_writelane_b32 v255, s6, 23
	v_writelane_b32 v255, s4, 24
	s_addk_i32 s4, 0xf700
	s_lshl_b32 s5, s2, 7
	v_writelane_b32 v255, s4, 25
	v_writelane_b32 v255, s5, 26
	s_add_i32 s4, s5, 0xffffb800
	v_writelane_b32 v255, s4, 27
	s_add_i32 s4, 0, 0x23f20
	v_writelane_b32 v255, s4, 28
	s_add_i32 s4, 0, 0x23f24
	v_writelane_b32 v255, s4, 29
	s_add_i32 s4, 0, 0x10100
	v_writelane_b32 v255, s4, 30
	s_add_i32 s4, 0, 0x2100
	v_writelane_b32 v255, s4, 31
	s_mov_b32 s4, s8
	s_ashr_i32 s9, s8, 31
	v_writelane_b32 v255, s4, 32
	s_mov_b64 s[14:15], 0x80
	v_mbcnt_lo_u32_b32 v1, -1, 0
	v_writelane_b32 v255, s5, 33
	s_lshl_b64 s[4:5], s[8:9], 18
	v_writelane_b32 v255, s4, 34
	v_mbcnt_hi_u32_b32 v244, -1, v1
	s_mov_b64 s[16:17], 0x1800
	v_writelane_b32 v255, s5, 35
	v_writelane_b32 v255, s88, 36
	s_mov_b32 s4, s57
	s_nop 0
	v_writelane_b32 v255, s89, 37
	v_writelane_b32 v255, s96, 38
	s_nop 1
	v_writelane_b32 v255, s97, 39
	v_writelane_b32 v255, s92, 40
	s_nop 1
	v_writelane_b32 v255, s93, 41
	s_branch .LBB0_452

; #define GAS __attribute__((address_space(1)))
; template <class Epi, class Sched, bool ALIGN_EPI, bool SP2>
; __device__ __forceinline__ void gemm_phase(LAS unsigned char* lds, const int tid, const Gemm g, const Sched& S, const Epi& E) {
;     const int wid = __builtin_amdgcn_readfirstlane(tid >> 6), lane = tid & 63, wr = wid >> 2, wc = wid & 3, fr = lane & 15, fq = lane >> 4;
;     const int nt0 = g.K / BK;
;     unsigned voffA[2], voffB[2];
; #pragma unroll
;     for (int i = 0; i < 2; ++i) { int R, C; stage_rc(tid * 16 + i * 8192, R, C); const int Rb = Epi::PERM ? ((R & ~31) + perm32(R & 31)) : R;
;         voffA[i] = (unsigned)(R * g.lda + C) * 2u; voffB[i] = (unsigned)(Rb * g.ldb + C) * 2u; }
;     const size_t kstep = (size_t)(BK * 2);
;     const size_t hstepA = (size_t)HALF * g.lda * 2, hstepB = (size_t)HALF * g.ldb * 2;
;     const unsigned ldsw = (unsigned)wid * 1024u;
;     const int aoff = lds_byte(wr * 64 + fr, fq * 8), boff = lds_byte(wc * 32 + fr, fq * 8);
;     ...
;     Unit cur, nxt; int ui = 0;
;     if (!S.next(0, cur)) return;
;     if (wr == 1) __builtin_amdgcn_s_setprio(1);
;     f32x4 acc[2][2][4][2];
; #pragma unroll
;     for (int a = 0; a < 2; ++a)
; #pragma unroll
;         for (int b = 0; b < 2; ++b)
; #pragma unroll
;             for (int m = 0; m < 4; ++m)
; #pragma unroll
;                 for (int n = 0; n < 2; ++n) acc[a][b][m][n] = (f32x4){0.f, 0.f, 0.f, 0.f};
;     bf16x8 At[4][2], B0[2][2], B1[2][2];
;     const GAS char* cA = S.aptr(cur); const GAS char* cB = S.bptr(cur);
;     if constexpr (SP2) {
;         PG8_STAGE(PG8_SB(0, 0), cB, voffB); PG8_STAGE(PG8_SB(0, 1), cB + hstepB, voffB); PG8_STAGE(PG8_SA(0, 0), cA, voffA); PG8_STAGE(PG8_SA(0, 1), cA + hstepA, voffA);
;         if (wr == 1) PG8_BAR;
;         PG8_WAIT_V(2); PG8_BAR;
;         PG8_STAGE(PG8_SB(1, 0), cB + kstep, voffB); PG8_STAGE(PG8_SA(1, 0), cA + kstep, voffA); PG8_STAGE(PG8_SB(1, 1), cB + hstepB + kstep, voffB);
;         PG8_WAIT_V(6); PG8_BAR;
;     } else {
;         PG8_STAGE(PG8_SB(0, 0), cB, voffB); PG8_STAGE(PG8_SA(0, 0), cA, voffA); PG8_STAGE(PG8_SB(0, 1), cB + hstepB, voffB); PG8_STAGE(PG8_SA(0, 1), cA + hstepA, voffA);
;         if (wr == 1) PG8_BAR;
;         PG8_WAIT_V(4); PG8_BAR;
;         const int s = i & 7, dir = ch & 1, bh = ch >> 1; u.z = bh * 9 + (dir == 0 ? s : (s == 0 ? 0 : 9 - s)); u.pn = dir; u.pm = s; return true; }
.LBB0_737:
	s_waitcnt vmcnt(0)
	v_bfe_i32 v3, v0, 27, 1
	v_lshlrev_b32_e32 v1, 4, v0
	v_lshrrev_b32_e32 v3, 22, v3
	v_add_u32_e32 v3, v1, v3
	v_and_b32_e32 v3, 0xfffffc00, v3
	v_sub_u32_e32 v3, v1, v3
	v_lshrrev_b32_e32 v4, 4, v3
	v_ashrrev_i32_e32 v2, 31, v0
	v_bitop3_b32 v3, v4, v3, 32 bitop3:0x6c
	v_lshrrev_b32_e32 v2, 26, v2
	v_ashrrev_i32_e32 v5, 31, v3
	v_add_u32_e32 v2, v0, v2
	v_lshrrev_b32_e32 v5, 26, v5
	v_ashrrev_i32_e32 v2, 6, v2
	v_add_u32_e32 v5, v3, v5
	v_lshlrev_b32_e32 v4, 3, v2
	s_waitcnt vmcnt(22)
	v_ashrrev_i32_e32 v6, 6, v5
	v_and_b32_e32 v5, 0xc0, v5
	v_and_b32_e32 v4, -16, v4
	v_lshlrev_b32_e32 v2, 5, v2
	v_sub_u32_e32 v3, v3, v5
	v_add_u32_e32 v4, v6, v4
	v_and_b32_e32 v2, 32, v2
	v_ashrrev_i16_sdwa v3, v205, sext(v3) dst_sel:DWORD dst_unused:UNUSED_PAD src0_sel:DWORD src1_sel:BYTE_0
	v_add_u32_sdwa v2, v2, sext(v3) dst_sel:DWORD dst_unused:UNUSED_PAD src0_sel:DWORD src1_sel:WORD_0
	v_lshlrev_b32_e32 v3, 1, v4
	v_lshrrev_b32_e32 v5, 2, v4
	v_and_b32_e32 v6, 3, v6
	s_mov_b32 s5, 0x7fffe0
	s_movk_i32 s4, 0x300
	v_and_b32_e32 v3, 24, v3
	v_and_b32_e32 v5, 4, v5
	v_and_or_b32 v6, v4, s5, v6
	v_mul_lo_u32 v4, v4, s4
	v_or3_b32 v3, v6, v5, v3
	v_add_lshl_u32 v130, v2, v4, 1
	v_lshlrev_b32_e32 v2, 1, v2
	v_add_u32_e32 v1, 0x2000, v1
	v_lshl_add_u32 v202, v3, 9, v2
	v_ashrrev_i32_e32 v2, 31, v1
	v_lshrrev_b32_e32 v2, 22, v2
	v_add_u32_e32 v2, v1, v2
	v_ashrrev_i32_e32 v2, 10, v2
	v_mul_i32_i24_e32 v3, 0x400, v2
	v_sub_u32_e32 v1, v1, v3
	v_lshrrev_b32_e32 v3, 4, v1
	v_bitop3_b32 v1, v3, v1, 32 bitop3:0x6c
	v_ashrrev_i32_e32 v4, 31, v1
	v_lshrrev_b32_e32 v4, 26, v4
	v_add_u32_e32 v4, v1, v4
	v_lshlrev_b32_e32 v3, 3, v2
	v_ashrrev_i32_e32 v5, 6, v4
	v_and_b32_e32 v4, 0xc0, v4
	v_and_b32_e32 v3, -16, v3
	v_lshlrev_b32_e32 v2, 5, v2
	v_sub_u32_e32 v1, v1, v4
	v_add_u32_e32 v3, v5, v3
	v_and_b32_e32 v2, 32, v2
	v_ashrrev_i16_sdwa v1, v205, sext(v1) dst_sel:DWORD dst_unused:UNUSED_PAD src0_sel:DWORD src1_sel:BYTE_0
	v_and_b32_e32 v5, 3, v5
	s_ashr_i32 s12, s10, 6
	v_add_u32_sdwa v1, v2, sext(v1) dst_sel:DWORD dst_unused:UNUSED_PAD src0_sel:DWORD src1_sel:WORD_0
	v_lshlrev_b32_e32 v2, 1, v3
	v_lshrrev_b32_e32 v4, 2, v3
	v_and_or_b32 v5, v3, s5, v5
	v_mul_lo_u32 v3, v3, s4
	s_lshl_b32 s4, s12, 10
	s_add_u32 s5, s6, 0x40600000
	s_addc_u32 s52, s7, 0
	s_add_u32 s53, s6, 0x43c00000
	s_addc_u32 s54, s7, 0
	s_lshr_b32 s101, s2, 5
	s_mul_i32 s101, s101, 0x30000
	s_add_u32 s5, s5, s101
	s_addc_u32 s52, s52, 0
	v_readlane_b32 s6, v254, 25
	v_readlane_b32 s7, v254, 26
	s_add_u32 s6, s53, s6
	s_addc_u32 s7, s54, s7
	v_readlane_b32 s13, v254, 22
	s_add_u32 s18, s6, s13
	s_addc_u32 s19, s7, 0
	s_add_i32 s55, s4, 0
	v_and_b32_e32 v2, 24, v2
	v_and_b32_e32 v4, 4, v4
	s_add_i32 m0, s55, 0x10000
	v_or3_b32 v2, v5, v4, v2
	v_add_lshl_u32 v132, v1, v3, 1
	v_lshlrev_b32_e32 v1, 1, v1
	global_load_lds_dwordx4 v202, s[18:19]
	s_add_i32 m0, s55, 0x12000
	v_lshl_add_u32 v134, v2, 9, v1
	s_add_u32 s6, s18, 0x10000
	global_load_lds_dwordx4 v134, s[18:19]
	s_addc_u32 s7, s19, 0
	s_add_i32 m0, s55, 0x14000
	v_cndmask_b32_e64 v1, 0, 1, s[8:9]
	global_load_lds_dwordx4 v202, s[6:7]
	s_add_i32 m0, s55, 0x16000
	s_movk_i32 s24, 0x300
	global_load_lds_dwordx4 v134, s[6:7]
	v_readlane_b32 s6, v255, 16
	s_add_u32 s22, s5, s6
	v_readlane_b32 s6, v254, 23
	s_mul_hi_i32 s6, s6, 0x60000
	s_addc_u32 s23, s52, s6
	s_add_i32 s60, s55, 0x2000
	v_readlane_b32 s7, v254, 24
	s_mov_b32 m0, s55
	s_add_u32 s6, s22, 0x30000
	global_load_lds_dwordx4 v130, s[22:23]
	s_mov_b32 m0, s60
	s_addc_u32 s7, s23, 0
	s_add_i32 s61, s55, 0x4000
	global_load_lds_dwordx4 v132, s[22:23]
	s_mov_b32 m0, s61
	s_add_i32 s62, s55, 0x6000
	global_load_lds_dwordx4 v130, s[6:7]
	s_mov_b32 m0, s62
	v_cmp_ne_u32_e64 s[38:39], 1, v1
	global_load_lds_dwordx4 v132, s[6:7]
	s_andn2_b64 vcc, exec, s[8:9]
	s_cbranch_vccnz .LBB0_739
	s_barrier

;         const int s = i & 7, dir = ch & 1, bh = ch >> 1; u.z = bh * 9 + (dir == 0 ? s : (s == 0 ? 0 : 9 - s)); u.pn = dir; u.pm = s; return true; }
.LBB0_743:
	s_add_i32 s69, s69, 1
	s_lshr_b32 s9, s69, 3
	s_mul_i32 s9, s9, s3
	s_and_b32 s101, s2, 31
	s_add_i32 s9, s9, s101
	s_cmp_lt_i32 s9, 32
	s_cselect_b64 s[24:25], -1, 0
	s_cmp_gt_i32 s9, 31
	s_cbranch_scc1 .LBB0_745
	s_and_b32 s68, s69, 7
	s_and_b32 s65, s9, 1
	s_ashr_i32 s8, s9, 1
	s_sub_i32 s9, 9, s68
	s_cmp_lg_u32 s68, 0
	s_cselect_b32 s9, s9, 0
	s_cmp_eq_u32 s65, 0
	s_mul_i32 s8, s8, 9
	s_cselect_b32 s9, s68, s9
	s_add_i32 s8, s9, s8

; #define PG8_STAGE(bufoff, gbase, voff) do { _Pragma("unroll") for (int _i = 0; _i < 2; ++_i) \
;         __builtin_amdgcn_global_load_lds((const GAS unsigned*)((const GAS char*)(gbase) + (voff)[_i]), (LAS unsigned*)(lds + (bufoff) + ldsw + _i * 8192), 16, 0, 0); } while (0)
; #define PG8_LDA(dst, b, h) do { _Pragma("unroll") for (int m = 0; m < 4; ++m) _Pragma("unroll") for (int k = 0; k < 2; ++k) dst[m][k] = *(const LAS bf16x8*)(lds + PG8_SA(b, h) + aoff + m * 2048 + k * 1024); } while (0)
; #define PG8_LDB(dst, b, h) do { _Pragma("unroll") for (int n = 0; n < 2; ++n) _Pragma("unroll") for (int k = 0; k < 2; ++k) dst[n][k] = *(const LAS bf16x8*)(lds + PG8_SB(b, h) + boff + n * 2048 + k * 1024); } while (0)
; #define PG8_MMA(ai, bj, At, Bt) do { __builtin_amdgcn_sched_barrier(0); _Pragma("unroll") for (int m = 0; m < 4; ++m) _Pragma("unroll") for (int n = 0; n < 2; ++n) _Pragma("unroll") for (int k = 0; k < 2; ++k) \
;         acc[ai][bj][m][n] = __builtin_amdgcn_mfma_f32_16x16x32_bf16(Bt[n][k], At[m][k], acc[ai][bj][m][n], 0, 0, 0); __builtin_amdgcn_sched_barrier(0); } while (0)
; #define PG8_WAIT_V(n) asm volatile("s_waitcnt vmcnt(" #n ")" ::: "memory")
; template <class Epi, class Sched, bool ALIGN_EPI, bool SP2>
; __device__ __forceinline__ void gemm_phase(LAS unsigned char* lds, const int tid, const Gemm g, const Sched& S, const Epi& E) {
;     ...
;             PG8_LDB(B0, 0, 0); PG8_LDB(B1, 0, 1); PG8_SCHED; PG8_LDA(At, 0, 0); PG8_STAGE(PG8_SA(1, 1), a1 + hstepA, voffA);
;             PG8_WAIT_V(8); PG8_WAIT_L(0); PG8_BAR; PG8_MMA(0, 0, At, B0); PG8_MMA(0, 1, At, B1); PG8_BAR; PG8_SCHED;
;             PG8_LDA(At, 0, 1); PG8_STAGE(PG8_SB(0, 0), b2, voffB); PG8_STAGE(PG8_SB(0, 1), b2 + hstepB, voffB); PG8_STAGE(PG8_SA(0, 0), a2, voffA);
;             PG8_WAIT_V(8); PG8_WAIT_L(0); PG8_BAR; PG8_MMA(1, 0, At, B0); PG8_MMA(1, 1, At, B1); PG8_BAR; PG8_SCHED;
;             PG8_LDB(B0, 1, 0); PG8_LDB(B1, 1, 1); PG8_SCHED; PG8_LDA(At, 1, 0); PG8_STAGE(PG8_SA(0, 1), a2 + hstepA, voffA);
;             PG8_WAIT_V(8); PG8_WAIT_L(0); PG8_BAR; PG8_MMA(0, 0, At, B0); PG8_MMA(0, 1, At, B1); PG8_BAR; PG8_SCHED;
;             PG8_LDA(At, 1, 1); PG8_STAGE(PG8_SB(1, 0), b3, voffB); PG8_STAGE(PG8_SB(1, 1), b3 + hstepB, voffB); PG8_STAGE(PG8_SA(1, 0), a3, voffA);
;             PG8_WAIT_V(8); PG8_WAIT_L(0); PG8_BAR; PG8_MMA(1, 0, At, B0); PG8_MMA(1, 1, At, B1); PG8_BAR; PG8_SCHED;
.Lch_rj1:
	s_waitcnt lgkmcnt(0)
	s_barrier
	s_waitcnt lgkmcnt(0)
	v_mfma_f32_16x16x32_bf16 v[126:129], v[142:145], v[174:177], v[126:129]
	v_mfma_f32_16x16x32_bf16 v[122:125], v[150:153], v[174:177], v[122:125]
	v_mfma_f32_16x16x32_bf16 v[118:121], v[142:145], v[182:185], v[118:121]
	v_mfma_f32_16x16x32_bf16 v[114:117], v[150:153], v[182:185], v[114:117]
	v_mfma_f32_16x16x32_bf16 v[110:113], v[142:145], v[190:193], v[110:113]
	v_mfma_f32_16x16x32_bf16 v[106:109], v[150:153], v[190:193], v[106:109]
	v_mfma_f32_16x16x32_bf16 v[102:105], v[142:145], v[198:201], v[102:105]
	v_mfma_f32_16x16x32_bf16 v[98:101], v[150:153], v[198:201], v[98:101]
	v_mfma_f32_16x16x32_bf16 v[126:129], v[146:149], v[178:181], v[126:129]
	v_mfma_f32_16x16x32_bf16 v[122:125], v[154:157], v[178:181], v[122:125]
	v_mfma_f32_16x16x32_bf16 v[118:121], v[146:149], v[186:189], v[118:121]
	v_mfma_f32_16x16x32_bf16 v[114:117], v[154:157], v[186:189], v[114:117]
	v_mfma_f32_16x16x32_bf16 v[110:113], v[146:149], v[194:197], v[110:113]
	v_mfma_f32_16x16x32_bf16 v[106:109], v[154:157], v[194:197], v[106:109]
	v_mfma_f32_16x16x32_bf16 v[102:105], v[146:149], v[214:217], v[102:105]
	v_mfma_f32_16x16x32_bf16 v[98:101], v[154:157], v[214:217], v[98:101]
	v_mfma_f32_16x16x32_bf16 v[94:97], v[158:161], v[174:177], v[94:97]
	v_mfma_f32_16x16x32_bf16 v[90:93], v[166:169], v[174:177], v[90:93]
	v_mfma_f32_16x16x32_bf16 v[86:89], v[158:161], v[182:185], v[86:89]
	v_mfma_f32_16x16x32_bf16 v[82:85], v[166:169], v[182:185], v[82:85]
	v_mfma_f32_16x16x32_bf16 v[78:81], v[158:161], v[190:193], v[78:81]
	v_mfma_f32_16x16x32_bf16 v[74:77], v[166:169], v[190:193], v[74:77]
	v_mfma_f32_16x16x32_bf16 v[70:73], v[158:161], v[198:201], v[70:73]
	v_mfma_f32_16x16x32_bf16 v[66:69], v[166:169], v[198:201], v[66:69]
	v_mfma_f32_16x16x32_bf16 v[94:97], v[162:165], v[178:181], v[94:97]
	v_mfma_f32_16x16x32_bf16 v[90:93], v[170:173], v[178:181], v[90:93]
	v_mfma_f32_16x16x32_bf16 v[86:89], v[162:165], v[186:189], v[86:89]
	v_mfma_f32_16x16x32_bf16 v[82:85], v[170:173], v[186:189], v[82:85]
	v_mfma_f32_16x16x32_bf16 v[78:81], v[162:165], v[194:197], v[78:81]
	v_mfma_f32_16x16x32_bf16 v[74:77], v[170:173], v[194:197], v[74:77]
	v_mfma_f32_16x16x32_bf16 v[70:73], v[162:165], v[214:217], v[70:73]
	v_mfma_f32_16x16x32_bf16 v[66:69], v[170:173], v[214:217], v[66:69]
	s_barrier
	s_mov_b32 m0, s93
	v_lshl_add_u64 v[138:139], s[44:45], 0, v[202:203]
	global_load_lds_dwordx4 v[138:139], off
	v_lshl_add_u64 v[218:219], s[44:45], 0, v[134:135]
	s_mov_b32 m0, s85
	v_lshl_add_u64 v[220:221], s[46:47], 0, v[202:203]
	global_load_lds_dwordx4 v[218:219], off
	s_mov_b32 m0, s92
	v_lshl_add_u64 v[222:223], s[42:43], 0, v[132:133]
	global_load_lds_dwordx4 v[220:221], off
	v_lshl_add_u64 v[220:221], s[46:47], 0, v[134:135]
	s_mov_b32 m0, s91
	s_nop 0
	global_load_lds_dwordx4 v[220:221], off
	v_lshl_add_u64 v[220:221], s[42:43], 0, v[130:131]
	s_mov_b32 m0, s55
	s_nop 0
	global_load_lds_dwordx4 v[220:221], off
	s_mov_b32 m0, s60
	s_nop 0
	global_load_lds_dwordx4 v[222:223], off
	s_cmp_lg_u32 s100, 0
	s_cbranch_scc1 .Lch_rw2
	s_waitcnt vmcnt(8)
.Lch_rj2:
	s_mov_b32 s100, 0
	s_waitcnt lgkmcnt(0)
	s_barrier
	s_waitcnt lgkmcnt(0)
	s_barrier
	v_add_u32_e32 v136, s82, v1
	ds_read_b128 v[142:145], v136
	ds_read_b128 v[146:149], v136 offset:1024
	ds_read_b128 v[150:153], v136 offset:2048
	ds_read_b128 v[154:157], v136 offset:3072
	v_add_u32_e32 v136, s73, v1
	ds_read_b128 v[158:161], v136
	ds_read_b128 v[162:165], v136 offset:1024
	ds_read_b128 v[166:169], v136 offset:2048
	ds_read_b128 v[170:173], v136 offset:3072
	s_mov_b32 m0, s61
	v_lshl_add_u64 v[224:225], s[34:35], 0, v[130:131]
	ds_read_b128 v[174:177], v140 offset:32768
	ds_read_b128 v[178:181], v140 offset:33792
	ds_read_b128 v[182:185], v140 offset:34816
	ds_read_b128 v[186:189], v140 offset:35840
	ds_read_b128 v[190:193], v140 offset:36864
	ds_read_b128 v[194:197], v140 offset:37888
	ds_read_b128 v[198:201], v140 offset:38912
	ds_read_b128 v[214:217], v140 offset:39936
	global_load_lds_dwordx4 v[224:225], off
	v_lshl_add_u64 v[224:225], s[34:35], 0, v[132:133]
	s_mov_b32 m0, s62
	s_nop 0
	global_load_lds_dwordx4 v[224:225], off
	s_waitcnt vmcnt(8)
	s_waitcnt lgkmcnt(0)
	s_barrier
	s_waitcnt lgkmcnt(0)
	v_mfma_f32_16x16x32_bf16 v[126:129], v[142:145], v[174:177], v[126:129]
	v_mfma_f32_16x16x32_bf16 v[122:125], v[150:153], v[174:177], v[122:125]
	v_mfma_f32_16x16x32_bf16 v[118:121], v[142:145], v[182:185], v[118:121]
	v_mfma_f32_16x16x32_bf16 v[114:117], v[150:153], v[182:185], v[114:117]
	v_mfma_f32_16x16x32_bf16 v[110:113], v[142:145], v[190:193], v[110:113]
	v_mfma_f32_16x16x32_bf16 v[106:109], v[150:153], v[190:193], v[106:109]
	v_mfma_f32_16x16x32_bf16 v[102:105], v[142:145], v[198:201], v[102:105]
	v_mfma_f32_16x16x32_bf16 v[98:101], v[150:153], v[198:201], v[98:101]
	v_mfma_f32_16x16x32_bf16 v[126:129], v[146:149], v[178:181], v[126:129]
	v_mfma_f32_16x16x32_bf16 v[122:125], v[154:157], v[178:181], v[122:125]
	v_mfma_f32_16x16x32_bf16 v[118:121], v[146:149], v[186:189], v[118:121]
	v_mfma_f32_16x16x32_bf16 v[114:117], v[154:157], v[186:189], v[114:117]
	v_mfma_f32_16x16x32_bf16 v[110:113], v[146:149], v[194:197], v[110:113]
	v_mfma_f32_16x16x32_bf16 v[106:109], v[154:157], v[194:197], v[106:109]
	v_mfma_f32_16x16x32_bf16 v[102:105], v[146:149], v[214:217], v[102:105]
	v_mfma_f32_16x16x32_bf16 v[98:101], v[154:157], v[214:217], v[98:101]
	v_mfma_f32_16x16x32_bf16 v[94:97], v[158:161], v[174:177], v[94:97]
	v_mfma_f32_16x16x32_bf16 v[90:93], v[166:169], v[174:177], v[90:93]
	v_mfma_f32_16x16x32_bf16 v[86:89], v[158:161], v[182:185], v[86:89]
	v_mfma_f32_16x16x32_bf16 v[82:85], v[166:169], v[182:185], v[82:85]
	v_mfma_f32_16x16x32_bf16 v[78:81], v[158:161], v[190:193], v[78:81]
	v_mfma_f32_16x16x32_bf16 v[74:77], v[166:169], v[190:193], v[74:77]
	v_mfma_f32_16x16x32_bf16 v[70:73], v[158:161], v[198:201], v[70:73]
	v_mfma_f32_16x16x32_bf16 v[66:69], v[166:169], v[198:201], v[66:69]
	v_mfma_f32_16x16x32_bf16 v[94:97], v[162:165], v[178:181], v[94:97]
	v_mfma_f32_16x16x32_bf16 v[90:93], v[170:173], v[178:181], v[90:93]
	v_mfma_f32_16x16x32_bf16 v[86:89], v[162:165], v[186:189], v[86:89]
	v_mfma_f32_16x16x32_bf16 v[82:85], v[170:173], v[186:189], v[82:85]
	v_mfma_f32_16x16x32_bf16 v[78:81], v[162:165], v[194:197], v[78:81]
	v_mfma_f32_16x16x32_bf16 v[74:77], v[170:173], v[194:197], v[74:77]
	v_mfma_f32_16x16x32_bf16 v[70:73], v[162:165], v[214:217], v[70:73]
	v_mfma_f32_16x16x32_bf16 v[66:69], v[170:173], v[214:217], v[66:69]
	s_barrier
; #define GAS __attribute__((address_space(1)))
; #define PG8_STAGE(bufoff, gbase, voff) do { _Pragma("unroll") for (int _i = 0; _i < 2; ++_i) \
;         __builtin_amdgcn_global_load_lds((const GAS unsigned*)((const GAS char*)(gbase) + (voff)[_i]), (LAS unsigned*)(lds + (bufoff) + ldsw + _i * 8192), 16, 0, 0); } while (0)
; #define PG8_LDA(dst, b, h) do { _Pragma("unroll") for (int m = 0; m < 4; ++m) _Pragma("unroll") for (int k = 0; k < 2; ++k) dst[m][k] = *(const LAS bf16x8*)(lds + PG8_SA(b, h) + aoff + m * 2048 + k * 1024); } while (0)
; #define PG8_MMA(ai, bj, At, Bt) do { __builtin_amdgcn_sched_barrier(0); _Pragma("unroll") for (int m = 0; m < 4; ++m) _Pragma("unroll") for (int n = 0; n < 2; ++n) _Pragma("unroll") for (int k = 0; k < 2; ++k) \
;         acc[ai][bj][m][n] = __builtin_amdgcn_mfma_f32_16x16x32_bf16(Bt[n][k], At[m][k], acc[ai][bj][m][n], 0, 0, 0); __builtin_amdgcn_sched_barrier(0); } while (0)
; #define PG8_WAIT_V(n) asm volatile("s_waitcnt vmcnt(" #n ")" ::: "memory")
; #define PG8_WAIT_L(n) asm volatile("s_waitcnt lgkmcnt(" #n ")" ::: "memory")
; #define PG8_BAR __builtin_amdgcn_s_barrier()
; #define PG8_SCHED __builtin_amdgcn_sched_barrier(0)
; template <class Epi, class Sched, bool ALIGN_EPI, bool SP2>
; __device__ __forceinline__ void gemm_phase(LAS unsigned char* lds, const int tid, const Gemm g, const Sched& S, const Epi& E) {
;     ...
;             PG8_LDA(At, 1, 1); PG8_STAGE(PG8_SB(1, 0), b3, voffB); PG8_STAGE(PG8_SB(1, 1), b3 + hstepB, voffB); PG8_STAGE(PG8_SA(1, 0), a3, voffA);
;             PG8_WAIT_V(8); PG8_WAIT_L(0); PG8_BAR; PG8_MMA(1, 0, At, B0); PG8_MMA(1, 1, At, B1); PG8_BAR; PG8_SCHED;
;     __device__ __forceinline__ void operator()(f32x4 (&acc)[2][2][4][2], const Unit& u, int wr, int wc, int fr, int fq) const {
;     ...
;         if (s == 0) {
;             GAS bf16_t* d0 = BB + (size_t)(bh * 9) * 256 * 768 + eoff;
; #pragma unroll
;             for (int ai = 0; ai < 2; ++ai)
; #pragma unroll
;                 for (int m = 0; m < 4; ++m)
; #pragma unroll
;                     for (int bj = 0; bj < 2; ++bj) *(GAS u32x4*)(d0 + (size_t)(ai * HALF + m * 16) * 768 + bj * HALF) = (u32x4){0u, 0u, 0u, 0u};
;         }
	s_mov_b32 m0, s72
	v_lshl_add_u64 v[138:139], v[138:139], 0, s[14:15]
	global_load_lds_dwordx4 v[138:139], off
	v_lshl_add_u64 v[138:139], v[218:219], 0, s[14:15]
	s_mov_b32 m0, s59
	s_nop 0
	global_load_lds_dwordx4 v[138:139], off
	v_lshl_add_u64 v[138:139], s[26:27], 0, v[202:203]
	s_mov_b32 m0, s95
	s_nop 0
	global_load_lds_dwordx4 v[138:139], off
	v_lshl_add_u64 v[138:139], s[26:27], 0, v[134:135]
	s_mov_b32 m0, s94
	s_nop 0
	global_load_lds_dwordx4 v[138:139], off
	v_lshl_add_u64 v[138:139], v[220:221], 0, s[14:15]
	s_mov_b32 m0, s63
	s_nop 0
	global_load_lds_dwordx4 v[138:139], off
	v_lshl_add_u64 v[138:139], v[222:223], 0, s[14:15]
	s_mov_b32 m0, s64
	s_nop 0
	global_load_lds_dwordx4 v[138:139], off
	s_waitcnt vmcnt(8)
	s_waitcnt lgkmcnt(0)
	s_barrier
	s_waitcnt lgkmcnt(0)
	s_barrier
	s_andn2_b64 vcc, exec, s[24:25]
	s_mov_b64 s[26:27], -1
	s_mov_b64 s[24:25], 0
	s_mov_b64 s[34:35], 0x100
	s_cbranch_vccz .LBB0_748
	s_and_b64 vcc, exec, s[6:7]
	s_cbranch_vccz .LBB0_751
	s_barrier
.LBB0_751:
	s_mul_hi_i32 s9, s56, 0x38e38e39
	s_lshr_b32 s18, s9, 31
	s_ashr_i32 s9, s9, 1
	s_add_i32 s9, s9, s18
	s_and_b32 s18, s9, 3
	s_lshl_b32 s19, s71, 4
	s_add_i32 s19, s19, 0
	s_lshl_b32 s18, s18, 2
	s_add_i32 s18, s19, s18
	s_add_i32 s18, s18, 0x20000
	v_mov_b32_e32 v136, s18
	ds_read_b32 v136, v136
	v_lshl_add_u32 v138, s71, 8, v137
	v_readlane_b32 s96, v255, 38
	v_readlane_b32 s92, v255, 40
	s_mul_i32 s9, s9, 9
	s_cmp_lg_u32 s70, 0
	v_ashrrev_i32_e32 v139, 31, v138
	v_readlane_b32 s97, v255, 39
	v_readlane_b32 s93, v255, 41
	s_movk_i32 s85, 0x7d7
	s_movk_i32 s86, 0xfe7f
	s_cbranch_scc1 .LBB0_753
	s_mul_i32 s18, s9, 0x60000
	s_mul_hi_i32 s19, s9, 0x60000
	s_add_u32 s18, s5, s18
	s_addc_u32 s19, s52, s19
	v_lshl_add_u64 v[142:143], v[138:139], 1, s[18:19]
	s_mov_b32 s58, s57
	s_mov_b32 s59, s57
	s_mov_b32 s56, s57
	v_mov_b64_e32 v[148:149], s[58:59]
	v_add_co_u32_e32 v144, vcc, 0x6000, v142
	v_mov_b64_e32 v[146:147], s[56:57]
	s_nop 0
	v_addc_co_u32_e32 v145, vcc, 0, v143, vcc
	global_store_dwordx4 v[142:143], v[146:149], off
	global_store_dwordx4 v[142:143], v[146:149], off offset:256
	global_store_dwordx4 v[144:145], v[146:149], off
	global_store_dwordx4 v[144:145], v[146:149], off offset:256
	v_add_co_u32_e32 v144, vcc, 0xc000, v142
	s_mov_b32 s18, 0x12000
	s_nop 0
	v_addc_co_u32_e32 v145, vcc, 0, v143, vcc
	global_store_dwordx4 v[144:145], v[146:149], off
	global_store_dwordx4 v[144:145], v[146:149], off offset:256
	v_add_co_u32_e32 v144, vcc, s18, v142
	s_nop 1
	v_addc_co_u32_e32 v145, vcc, 0, v143, vcc
	global_store_dwordx4 v[144:145], v[146:149], off
	global_store_dwordx4 v[144:145], v[146:149], off offset:256
	v_add_co_u32_e32 v144, vcc, 0x30000, v142
	s_nop 1
	v_addc_co_u32_e32 v145, vcc, 0, v143, vcc
	v_add_co_u32_e32 v144, vcc, 0x36000, v142
	s_nop 1
	v_addc_co_u32_e32 v145, vcc, 0, v143, vcc
	v_add_co_u32_e32 v144, vcc, 0x3c000, v142
	s_nop 1
	v_addc_co_u32_e32 v145, vcc, 0, v143, vcc
	v_add_co_u32_e32 v142, vcc, 0x42000, v142
	v_addc_co_u32_e32 v143, vcc, 0, v143, vcc
; #define GAS __attribute__((address_space(1)))
; __device__ __forceinline__ unsigned cvt_pk_bf16(float lo, float hi) { unsigned r; asm volatile("v_cvt_pk_bf16_f32 %0, %1, %2" : "=v"(r) : "v"(lo), "v"(hi)); return r; }
;     __device__ __forceinline__ void operator()(f32x4 (&acc)[2][2][4][2], const Unit& u, int wr, int wc, int fr, int fq) const {
;     ...
;         if (s == 0) {
;             GAS bf16_t* d0 = BB + (size_t)(bh * 9) * 256 * 768 + eoff;
; #pragma unroll
;             for (int ai = 0; ai < 2; ++ai)
; #pragma unroll
;                 for (int m = 0; m < 4; ++m)
; #pragma unroll
;                     for (int bj = 0; bj < 2; ++bj) *(GAS u32x4*)(d0 + (size_t)(ai * HALF + m * 16) * 768 + bj * HALF) = (u32x4){0u, 0u, 0u, 0u};
;         }
; #pragma unroll
;         for (int ai = 0; ai < 2; ++ai)
; #pragma unroll
;             for (int m = 0; m < 4; ++m) {
; #pragma unroll
;                 for (int bj = 0; bj < 2; ++bj) { const f32x4 v0 = acc[ai][bj][m][0], v1 = acc[ai][bj][m][1];
;                     u32x4 w; w.x = cvt_pk_bf16(v0[0], v0[1]); w.y = cvt_pk_bf16(v0[2], v0[3]); w.z = cvt_pk_bf16(v1[0], v1[1]); w.w = cvt_pk_bf16(v1[2], v1[3]);
;                     *(GAS u32x4*)(dst + (size_t)(ai * HALF + m * 16) * 768 + bj * HALF) = w;
;                     acc[ai][bj][m][0] = v0 * cdec; acc[ai][bj][m][1] = v1 * cdec; }
;                 asm volatile("" ::: "memory"); }
.LBB0_753:
	s_add_i32 s18, s70, 1
	s_sub_i32 s19, 8, s70
	s_cmp_eq_u32 s71, 0
	s_cselect_b32 s18, s18, s19
	s_add_i32 s9, s18, s9
	s_mul_hi_i32 s19, s9, 0x60000
	s_mul_i32 s9, s9, 0x60000
	s_add_u32 s18, s5, s9
	s_addc_u32 s19, s52, s19
	v_lshl_add_u64 v[138:139], v[138:139], 1, s[18:19]
	v_cvt_pk_bf16_f32 v142, v126, v127
	v_cvt_pk_bf16_f32 v143, v128, v129
	v_cvt_pk_bf16_f32 v144, v122, v123
	v_cvt_pk_bf16_f32 v145, v124, v125
	global_store_dwordx4 v[138:139], v[142:145], off
	v_add_co_u32_e32 v146, vcc, s74, v138
	s_nop 0
	v_cvt_pk_bf16_f32 v142, v94, v95
	v_cvt_pk_bf16_f32 v143, v96, v97
	v_cvt_pk_bf16_f32 v144, v90, v91
	v_cvt_pk_bf16_f32 v145, v92, v93
	global_store_dwordx4 v[138:139], v[142:145], off offset:256
	v_addc_co_u32_e32 v147, vcc, 0, v139, vcc
	s_nop 0
	v_cvt_pk_bf16_f32 v142, v118, v119
	v_cvt_pk_bf16_f32 v143, v120, v121
	v_cvt_pk_bf16_f32 v144, v114, v115
	v_cvt_pk_bf16_f32 v145, v116, v117
	s_mov_b32 s9, 0xc000
	global_store_dwordx4 v[146:147], v[142:145], off
	s_mov_b64 s[18:19], -1
	s_nop 0
	v_cvt_pk_bf16_f32 v142, v86, v87
	v_cvt_pk_bf16_f32 v143, v88, v89
	v_cvt_pk_bf16_f32 v144, v82, v83
	v_cvt_pk_bf16_f32 v145, v84, v85
	global_store_dwordx4 v[146:147], v[142:145], off offset:256
	v_add_co_u32_e32 v146, vcc, s9, v138
	s_nop 0
	v_cvt_pk_bf16_f32 v142, v110, v111
	v_cvt_pk_bf16_f32 v143, v112, v113
	v_cvt_pk_bf16_f32 v144, v106, v107
	v_cvt_pk_bf16_f32 v145, v108, v109
	s_nop 0
	v_addc_co_u32_e32 v147, vcc, 0, v139, vcc
	s_mov_b32 s9, 0x12000
	global_store_dwordx4 v[146:147], v[142:145], off
	s_nop 1
	v_cvt_pk_bf16_f32 v142, v78, v79
	v_cvt_pk_bf16_f32 v143, v80, v81
	v_cvt_pk_bf16_f32 v144, v74, v75
	v_cvt_pk_bf16_f32 v145, v76, v77
	global_store_dwordx4 v[146:147], v[142:145], off offset:256
	v_add_co_u32_e32 v146, vcc, s9, v138
	s_nop 0
	v_cvt_pk_bf16_f32 v142, v102, v103
	v_cvt_pk_bf16_f32 v143, v104, v105
	v_cvt_pk_bf16_f32 v144, v98, v99
	v_cvt_pk_bf16_f32 v145, v100, v101
	s_nop 0
	v_addc_co_u32_e32 v147, vcc, 0, v139, vcc
	s_mov_b32 s9, 0x30000
	global_store_dwordx4 v[146:147], v[142:145], off
	s_nop 1
	v_cvt_pk_bf16_f32 v142, v70, v71
	v_cvt_pk_bf16_f32 v143, v72, v73
	v_cvt_pk_bf16_f32 v144, v66, v67
	v_cvt_pk_bf16_f32 v145, v68, v69
	global_store_dwordx4 v[146:147], v[142:145], off offset:256
	v_add_co_u32_e32 v146, vcc, s9, v138
	s_nop 0
	v_cvt_pk_bf16_f32 v142, v62, v63
	v_cvt_pk_bf16_f32 v143, v64, v65
	v_cvt_pk_bf16_f32 v144, v58, v59
	v_cvt_pk_bf16_f32 v145, v60, v61
	s_nop 0
	v_addc_co_u32_e32 v147, vcc, 0, v139, vcc
	s_mov_b32 s9, 0x36000
	s_nop 1
	v_cvt_pk_bf16_f32 v142, v30, v31
	v_cvt_pk_bf16_f32 v143, v32, v33
	v_cvt_pk_bf16_f32 v144, v26, v27
	v_cvt_pk_bf16_f32 v145, v28, v29
	v_add_co_u32_e32 v146, vcc, s9, v138
	s_nop 0
	v_cvt_pk_bf16_f32 v142, v54, v55
	v_cvt_pk_bf16_f32 v143, v56, v57
	v_cvt_pk_bf16_f32 v144, v50, v51
	v_cvt_pk_bf16_f32 v145, v52, v53
	s_nop 0
	v_addc_co_u32_e32 v147, vcc, 0, v139, vcc
	s_mov_b32 s9, 0x3c000
	s_nop 1
	v_cvt_pk_bf16_f32 v142, v22, v23
	v_cvt_pk_bf16_f32 v143, v24, v25
	v_cvt_pk_bf16_f32 v144, v18, v19
	v_cvt_pk_bf16_f32 v145, v20, v21
	v_add_co_u32_e32 v146, vcc, s9, v138
	s_nop 0
	v_cvt_pk_bf16_f32 v142, v46, v47
	v_cvt_pk_bf16_f32 v143, v48, v49
	v_cvt_pk_bf16_f32 v144, v42, v43
	v_cvt_pk_bf16_f32 v145, v44, v45
	s_nop 0
	v_addc_co_u32_e32 v147, vcc, 0, v139, vcc
	s_mov_b32 s9, 0x42000
	v_add_co_u32_e32 v138, vcc, s9, v138
	s_nop 0
	v_cvt_pk_bf16_f32 v142, v14, v15
	v_cvt_pk_bf16_f32 v143, v16, v17
	v_cvt_pk_bf16_f32 v144, v10, v11
	v_cvt_pk_bf16_f32 v145, v12, v13
	v_addc_co_u32_e32 v139, vcc, 0, v139, vcc
	s_nop 0
	v_cvt_pk_bf16_f32 v142, v38, v39
	v_cvt_pk_bf16_f32 v143, v40, v41
	v_cvt_pk_bf16_f32 v144, v34, v35
	v_cvt_pk_bf16_f32 v145, v36, v37
	s_and_b64 vcc, exec, s[40:41]
	s_nop 0
	v_cvt_pk_bf16_f32 v142, v6, v7
	v_cvt_pk_bf16_f32 v143, v8, v9
	v_cvt_pk_bf16_f32 v144, v2, v3
	v_cvt_pk_bf16_f32 v145, v4, v5
	s_cbranch_vccnz .LBB0_742
	s_cmp_lg_u32 s70, 7
	s_cbranch_scc1 .LBB0_756
	s_mov_b32 s100, 0
	v_mov_b32_e32 v2, 0
	v_mov_b32_e32 v3, v2
	v_mov_b32_e32 v4, v2
	v_mov_b32_e32 v5, v2
	v_mov_b32_e32 v6, v2
	v_mov_b32_e32 v7, v2
	v_mov_b32_e32 v8, v2
	v_mov_b32_e32 v9, v2
	v_mov_b32_e32 v10, v2
	v_mov_b32_e32 v11, v2
	v_mov_b32_e32 v12, v2
	v_mov_b32_e32 v13, v2
	v_mov_b32_e32 v14, v2
	v_mov_b32_e32 v15, v2
	v_mov_b32_e32 v16, v2
	v_mov_b32_e32 v17, v2
	v_mov_b32_e32 v18, v2
	v_mov_b32_e32 v19, v2
	v_mov_b32_e32 v20, v2
	v_mov_b32_e32 v21, v2
	v_mov_b32_e32 v22, v2
	v_mov_b32_e32 v23, v2
	v_mov_b32_e32 v24, v2
	v_mov_b32_e32 v25, v2
	v_mov_b32_e32 v26, v2
	v_mov_b32_e32 v27, v2
	v_mov_b32_e32 v28, v2
	v_mov_b32_e32 v29, v2
	v_mov_b32_e32 v30, v2
	v_mov_b32_e32 v31, v2
	v_mov_b32_e32 v32, v2
	v_mov_b32_e32 v33, v2
	v_mov_b32_e32 v34, v2
	v_mov_b32_e32 v35, v2
	v_mov_b32_e32 v36, v2
	v_mov_b32_e32 v37, v2
	v_mov_b32_e32 v38, v2
	v_mov_b32_e32 v39, v2
	v_mov_b32_e32 v40, v2
	v_mov_b32_e32 v41, v2
	v_mov_b32_e32 v42, v2
	v_mov_b32_e32 v43, v2
	v_mov_b32_e32 v44, v2
	v_mov_b32_e32 v45, v2
	v_mov_b32_e32 v46, v2
	v_mov_b32_e32 v47, v2
	v_mov_b32_e32 v48, v2
	v_mov_b32_e32 v49, v2
	v_mov_b32_e32 v50, v2
	v_mov_b32_e32 v51, v2
	v_mov_b32_e32 v52, v2
	v_mov_b32_e32 v53, v2
	v_mov_b32_e32 v54, v2
	v_mov_b32_e32 v55, v2
	v_mov_b32_e32 v56, v2
	v_mov_b32_e32 v57, v2
	v_mov_b32_e32 v58, v2
	v_mov_b32_e32 v59, v2
	v_mov_b32_e32 v60, v2
	v_mov_b32_e32 v61, v2
	v_mov_b32_e32 v62, v2
	v_mov_b32_e32 v63, v2
	v_mov_b32_e32 v64, v2
	v_mov_b32_e32 v65, v2
	v_mov_b32_e32 v66, v2
	v_mov_b32_e32 v67, v2
	v_mov_b32_e32 v68, v2
	v_mov_b32_e32 v69, v2
	v_mov_b32_e32 v70, v2
	v_mov_b32_e32 v71, v2
	v_mov_b32_e32 v72, v2
	v_mov_b32_e32 v73, v2
	v_mov_b32_e32 v74, v2
	v_mov_b32_e32 v75, v2
	v_mov_b32_e32 v76, v2
	v_mov_b32_e32 v77, v2
	v_mov_b32_e32 v78, v2
	v_mov_b32_e32 v79, v2
	v_mov_b32_e32 v80, v2
	v_mov_b32_e32 v81, v2
	v_mov_b32_e32 v82, v2
	v_mov_b32_e32 v83, v2
	v_mov_b32_e32 v84, v2
	v_mov_b32_e32 v85, v2
	v_mov_b32_e32 v86, v2
	v_mov_b32_e32 v87, v2
	v_mov_b32_e32 v88, v2
	v_mov_b32_e32 v89, v2
	v_mov_b32_e32 v90, v2
	v_mov_b32_e32 v91, v2
	v_mov_b32_e32 v92, v2
	v_mov_b32_e32 v93, v2
	v_mov_b32_e32 v94, v2
	v_mov_b32_e32 v95, v2
	v_mov_b32_e32 v96, v2
	v_mov_b32_e32 v97, v2
	v_mov_b32_e32 v98, v2
	v_mov_b32_e32 v99, v2
	v_mov_b32_e32 v100, v2
	v_mov_b32_e32 v101, v2
	v_mov_b32_e32 v102, v2
	v_mov_b32_e32 v103, v2
	v_mov_b32_e32 v104, v2
	v_mov_b32_e32 v105, v2
	v_mov_b32_e32 v106, v2
	v_mov_b32_e32 v107, v2
	v_mov_b32_e32 v108, v2
	v_mov_b32_e32 v109, v2
	v_mov_b32_e32 v110, v2
	v_mov_b32_e32 v111, v2
	v_mov_b32_e32 v112, v2
	v_mov_b32_e32 v113, v2
	v_mov_b32_e32 v114, v2
	v_mov_b32_e32 v115, v2
	v_mov_b32_e32 v116, v2
	v_mov_b32_e32 v117, v2
	v_mov_b32_e32 v118, v2
	v_mov_b32_e32 v119, v2
	v_mov_b32_e32 v120, v2
	v_mov_b32_e32 v121, v2
	v_mov_b32_e32 v122, v2
	v_mov_b32_e32 v123, v2
	v_mov_b32_e32 v124, v2
	v_mov_b32_e32 v125, v2
	v_mov_b32_e32 v126, v2
	v_mov_b32_e32 v127, v2
	v_mov_b32_e32 v128, v2
	v_mov_b32_e32 v129, v2
	s_and_b64 vcc, exec, s[38:39]
	s_cbranch_vccnz .LBB0_741
	s_branch .LBB0_740

; #define LAS __attribute__((address_space(3)))
; #define REP(k) _Pragma("unroll 1") for (int _r = 0; _r < (((DUPMASK >> (k)) & 1u) ? 2 : 1); ++_r)
; #define LAUNDER() do { int _t = F.tid; asm volatile("" : "+v"(_t)); F.tid = _t; F.lane = _t & 63; F.wave = __builtin_amdgcn_readfirstlane(_t >> 6); \
;         asm volatile("" : "+s"(ap)); GAS unsigned char* _w = (GAS unsigned char*)ap->ws; asm volatile("" : "+s"(_w)); F.ws = _w; ws = _w; } while (0)
; template <bool CTX>
; __device__ __forceinline__ void conv_mfma(Frame& F, CArgs a, int l, int wblk, int nblk) {
;     ...
;     __syncthreads();
;     for (int e = tid; e < U_BYTES / 16; e += 512) *(LAS u32x4*)(lds + U_OFF + e * 16) = (u32x4){0u, 0u, 0u, 0u};
; __global__ void __launch_bounds__(512, 2) mk_fwd(Args args_unused) {
;     ...
;             REP(15) { LAUNDER(); if (F.G == 256) { if (F.blk >= 32) conv_phase(F, ap, l, F.blk - 32, 224); } else conv_phase(F, ap, l, F.blk, F.G); }
.LBB0_853:
	s_and_b64 vcc, exec, s[10:11]
	s_cbranch_vccz .LBB0_918
	s_cmp_gt_i32 s2, 63
	s_cselect_b64 s[10:11], -1, 0
	s_and_b64 vcc, exec, s[10:11]
	s_cbranch_vccz .LBB0_918
	s_movk_i32 s5, 0x9d8
	v_cmp_gt_i32_e32 vcc, s5, v0
	v_add_u32_e32 v1, 0xfffffe00, v0
	s_barrier
	s_and_saveexec_b64 s[10:11], vcc
	s_cbranch_execz .LBB0_858
	v_readlane_b32 s5, v255, 30
	v_add_u32_e32 v2, 0xfffffe00, v0
	s_mov_b64 s[18:19], 0
	v_lshl_add_u32 v3, v0, 4, s5

; template <bool CTX>
; __device__ __forceinline__ void conv_mfma(Frame& F, CArgs a, int l, int wblk, int nblk) {
;     ...
;     for (int ch = wblk; ch < 512; ch += nblk) {
.LBB0_860:
	s_or_b64 exec, exec, s[34:35]
	s_add_i32 s4, s56, 0xc0
	s_cmpk_lt_i32 s56, 0x140
	s_mov_b32 s56, s4
	s_cbranch_scc0 .LBB0_888

; template <bool CTX>
; __device__ __forceinline__ void conv_mfma(Frame& F, CArgs a, int l, int wblk, int nblk) {
;     ...
;     for (int ch = wblk; ch < 512; ch += nblk) {
.LBB0_896:
	s_or_b64 exec, exec, s[12:13]
	s_add_i32 s11, s10, 0xc0
	s_cmpk_lt_i32 s10, 0x140
	s_mov_b32 s10, s11
	s_cbranch_scc0 .LBB0_917
